# baseline (speedup 1.0000x reference)
.LBB0_897:
	s_and_b32 s28, s26, 0x10000
	v_or_b32_e32 v0, s28, v180
	v_add_u32_e32 v218, v0, v184
	v_add_u32_e32 v0, v0, v183
	s_waitcnt lgkmcnt(2)
	v_mfma_f32_16x16x32_bf16 v[158:161], v[2:5], v[202:205], v[158:161]
	v_add_u32_e32 v218, v218, v181
	s_add_i32 s27, s27, -1
	v_mfma_f32_16x16x32_bf16 v[154:157], v[6:9], v[202:205], v[154:157]
	s_add_i32 s26, s26, 0x10000
	v_mfma_f32_16x16x32_bf16 v[150:153], v[10:13], v[202:205], v[150:153]
	v_mfma_f32_16x16x32_bf16 v[146:149], v[14:17], v[202:205], v[146:149]
	ds_read_b128 v[202:205], v0 offset:6144
	s_waitcnt lgkmcnt(2)
	v_mfma_f32_16x16x32_bf16 v[142:145], v[2:5], v[206:209], v[142:145]
	v_mfma_f32_16x16x32_bf16 v[138:141], v[6:9], v[206:209], v[138:141]
	v_mfma_f32_16x16x32_bf16 v[134:137], v[10:13], v[206:209], v[134:137]
	v_mfma_f32_16x16x32_bf16 v[130:133], v[14:17], v[206:209], v[130:133]
	ds_read_b128 v[206:209], v0 offset:8192
	s_waitcnt lgkmcnt(2)
	v_mfma_f32_16x16x32_bf16 v[126:129], v[2:5], v[226:229], v[126:129]
	v_mfma_f32_16x16x32_bf16 v[122:125], v[6:9], v[226:229], v[122:125]
	v_mfma_f32_16x16x32_bf16 v[118:121], v[10:13], v[226:229], v[118:121]
	v_mfma_f32_16x16x32_bf16 v[114:117], v[14:17], v[226:229], v[114:117]
	ds_read_b128 v[226:229], v0 offset:10240
	s_waitcnt lgkmcnt(2)
	v_mfma_f32_16x16x32_bf16 v[106:109], v[2:5], v[202:205], v[106:109]
	v_mfma_f32_16x16x32_bf16 v[102:105], v[6:9], v[202:205], v[102:105]
	v_mfma_f32_16x16x32_bf16 v[98:101], v[10:13], v[202:205], v[98:101]
	v_mfma_f32_16x16x32_bf16 v[94:97], v[14:17], v[202:205], v[94:97]
	ds_read_b128 v[202:205], v0 offset:12288
	ds_read_b128 v[230:233], v218 offset:32768
	s_waitcnt lgkmcnt(3)
	v_mfma_f32_16x16x32_bf16 v[86:89], v[2:5], v[206:209], v[86:89]
	v_mfma_f32_16x16x32_bf16 v[82:85], v[6:9], v[206:209], v[82:85]
	v_mfma_f32_16x16x32_bf16 v[78:81], v[10:13], v[206:209], v[78:81]
	v_mfma_f32_16x16x32_bf16 v[74:77], v[14:17], v[206:209], v[74:77]
	ds_read_b128 v[206:209], v0 offset:14336
	ds_read_b128 v[234:237], v218 offset:34816
	v_add_u32_e32 v0, v0, v181
	s_waitcnt lgkmcnt(4)
	v_mfma_f32_16x16x32_bf16 v[70:73], v[2:5], v[226:229], v[70:73]
	v_mfma_f32_16x16x32_bf16 v[66:69], v[6:9], v[226:229], v[66:69]
	v_mfma_f32_16x16x32_bf16 v[62:65], v[10:13], v[226:229], v[62:65]
	v_mfma_f32_16x16x32_bf16 v[58:61], v[14:17], v[226:229], v[58:61]
	ds_read_b128 v[226:229], v0 offset:0
	ds_read_b128 v[238:241], v218 offset:36864
	s_waitcnt lgkmcnt(5)
	v_mfma_f32_16x16x32_bf16 v[54:57], v[2:5], v[202:205], v[54:57]
	v_mfma_f32_16x16x32_bf16 v[50:53], v[6:9], v[202:205], v[50:53]
	v_mfma_f32_16x16x32_bf16 v[46:49], v[10:13], v[202:205], v[46:49]
	v_mfma_f32_16x16x32_bf16 v[42:45], v[14:17], v[202:205], v[42:45]
	ds_read_b128 v[202:205], v0 offset:2048
	ds_read_b128 v[242:245], v218 offset:38912
	s_waitcnt lgkmcnt(5)
	v_mfma_f32_16x16x32_bf16 v[38:41], v[2:5], v[206:209], v[38:41]
	v_mfma_f32_16x16x32_bf16 v[34:37], v[6:9], v[206:209], v[34:37]
	v_mfma_f32_16x16x32_bf16 v[90:93], v[10:13], v[206:209], v[90:93]
	v_mfma_f32_16x16x32_bf16 v[110:113], v[14:17], v[206:209], v[110:113]
	ds_read_b128 v[186:189], v0 offset:4096
	s_waitcnt lgkmcnt(4)
	v_mfma_f32_16x16x32_bf16 v[158:161], v[230:233], v[226:229], v[158:161]
	v_mfma_f32_16x16x32_bf16 v[154:157], v[234:237], v[226:229], v[154:157]
	s_waitcnt lgkmcnt(3)
	v_mfma_f32_16x16x32_bf16 v[150:153], v[238:241], v[226:229], v[150:153]
	s_waitcnt lgkmcnt(1)
	v_mfma_f32_16x16x32_bf16 v[146:149], v[242:245], v[226:229], v[146:149]
	ds_read_b128 v[190:193], v0 offset:6144
	v_mfma_f32_16x16x32_bf16 v[142:145], v[230:233], v[202:205], v[142:145]
	v_mfma_f32_16x16x32_bf16 v[138:141], v[234:237], v[202:205], v[138:141]
	v_mfma_f32_16x16x32_bf16 v[134:137], v[238:241], v[202:205], v[134:137]
	v_mfma_f32_16x16x32_bf16 v[130:133], v[242:245], v[202:205], v[130:133]
	ds_read_b128 v[194:197], v0 offset:8192
	s_waitcnt lgkmcnt(2)
	v_mfma_f32_16x16x32_bf16 v[126:129], v[230:233], v[186:189], v[126:129]
	v_mfma_f32_16x16x32_bf16 v[122:125], v[234:237], v[186:189], v[122:125]
	v_mfma_f32_16x16x32_bf16 v[118:121], v[238:241], v[186:189], v[118:121]
	v_mfma_f32_16x16x32_bf16 v[114:117], v[242:245], v[186:189], v[114:117]
	ds_read_b128 v[186:189], v0 offset:10240
	s_waitcnt lgkmcnt(2)
	v_mfma_f32_16x16x32_bf16 v[106:109], v[230:233], v[190:193], v[106:109]
	v_mfma_f32_16x16x32_bf16 v[102:105], v[234:237], v[190:193], v[102:105]
	v_mfma_f32_16x16x32_bf16 v[98:101], v[238:241], v[190:193], v[98:101]
	v_mfma_f32_16x16x32_bf16 v[94:97], v[242:245], v[190:193], v[94:97]
	ds_read_b128 v[190:193], v0 offset:12288
	s_waitcnt lgkmcnt(2)
	v_mfma_f32_16x16x32_bf16 v[86:89], v[230:233], v[194:197], v[86:89]
	v_mfma_f32_16x16x32_bf16 v[82:85], v[234:237], v[194:197], v[82:85]
	v_mfma_f32_16x16x32_bf16 v[78:81], v[238:241], v[194:197], v[78:81]
	v_mfma_f32_16x16x32_bf16 v[74:77], v[242:245], v[194:197], v[74:77]
	ds_read_b128 v[194:197], v0 offset:14336
	s_waitcnt vmcnt(0) lgkmcnt(0)
	s_barrier
; template <int NT, int BM, int BN, bool PLAIN, int NSTAGE, bool EPI_LDS>
; __device__ __forceinline__ void gemm_tile(const Params& p, const GemmDesc& g, bf16_t* lds, const int tid) {
;     ...
;     if (PLAIN) {
;       int kt = 0;
;       for (; kt + 2 < nk; ++kt) {
;         const int cur = kt & 1;
;         COMPUTE_X(cur, 1, 1, kt + 2)
;         __syncthreads();
;       }
;       if (kt + 1 < nk) {
;         const int cur = kt & 1;
;         COMPUTE_X(cur, 1, 0, 0)
;         __syncthreads();
;         ++kt;
;       }
;       {
;         const int cur = kt & 1;
;         COMPUTE_X(cur, 0, 0, 0)
;         __syncthreads();
;       }
	s_xor_b32 s29, s28, 0x10000
	v_or_b32_e32 v18, s29, v180
	v_add_u32_e32 v19, v18, v184
	v_add_u32_e32 v18, v18, v183
	ds_read_b128 v[2:5], v19 offset:32768
	ds_read_b128 v[6:9], v19 offset:34816
	ds_read_b128 v[10:13], v19 offset:36864
	ds_read_b128 v[14:17], v19 offset:38912
	ds_read_b128 v[202:205], v18
	ds_read_b128 v[206:209], v18 offset:2048
	ds_read_b128 v[226:229], v18 offset:4096
	s_add_u32 m0, s28, s57
	v_mfma_f32_16x16x32_bf16 v[70:73], v[230:233], v[186:189], v[70:73]
	global_load_lds_dwordx4 v162, s[60:61]
	s_add_u32 m0, m0, 0x400
	v_mfma_f32_16x16x32_bf16 v[66:69], v[234:237], v[186:189], v[66:69]
	global_load_lds_dwordx4 v163, s[60:61]
	s_add_u32 m0, m0, 0x400
	v_mfma_f32_16x16x32_bf16 v[62:65], v[238:241], v[186:189], v[62:65]
	global_load_lds_dwordx4 v164, s[60:61]
	s_add_u32 m0, m0, 0x400
	v_mfma_f32_16x16x32_bf16 v[58:61], v[242:245], v[186:189], v[58:61]
	global_load_lds_dwordx4 v165, s[60:61]
	s_add_u32 m0, m0, 0x400
	v_mfma_f32_16x16x32_bf16 v[54:57], v[230:233], v[190:193], v[54:57]
	global_load_lds_dwordx4 v166, s[60:61]
	s_add_u32 m0, m0, 0x400
	v_mfma_f32_16x16x32_bf16 v[50:53], v[234:237], v[190:193], v[50:53]
	global_load_lds_dwordx4 v167, s[60:61]
	s_add_u32 m0, m0, 0x400
	v_mfma_f32_16x16x32_bf16 v[46:49], v[238:241], v[190:193], v[46:49]
	global_load_lds_dwordx4 v168, s[60:61]
	s_add_u32 m0, m0, 0x400
	v_mfma_f32_16x16x32_bf16 v[42:45], v[242:245], v[190:193], v[42:45]
	global_load_lds_dwordx4 v169, s[60:61]
	s_add_u32 s60, s60, 0x80
	s_addc_u32 s61, s61, 0
	v_mfma_f32_16x16x32_bf16 v[38:41], v[230:233], v[194:197], v[38:41]
	v_mfma_f32_16x16x32_bf16 v[34:37], v[234:237], v[194:197], v[34:37]
	v_mfma_f32_16x16x32_bf16 v[90:93], v[238:241], v[194:197], v[90:93]
	v_mfma_f32_16x16x32_bf16 v[110:113], v[242:245], v[194:197], v[110:113]
	s_cmp_lg_u32 s27, 0
	s_cbranch_scc1 .LBB0_897
	s_lshl_b32 s3, s3, 16
	s_and_b32 s3, s3, 0x10000
	v_or_b32_e32 v0, s3, v180
	v_add_u32_e32 v198, v0, v184
	ds_read_b128 v[162:165], v198 offset:32768
	ds_read_b128 v[166:169], v198 offset:34816
	ds_read_b128 v[170:173], v198 offset:36864
	ds_read_b128 v[186:189], v198 offset:38912
	v_add_u32_e32 v0, v0, v183
	ds_read_b128 v[174:177], v0
	ds_read_b128 v[190:193], v0 offset:2048
	ds_read_b128 v[194:197], v0 offset:4096
	s_waitcnt lgkmcnt(2)
	v_mfma_f32_16x16x32_bf16 v[30:33], v[162:165], v[174:177], v[158:161]
	s_not_b32 s3, s23
	s_lshl_b32 s3, s3, 16
	s_and_b32 s3, s3, 0x10000
	v_mfma_f32_16x16x32_bf16 v[154:157], v[166:169], v[174:177], v[154:157]
	s_cmp_lg_u32 s56, 9
	s_cselect_b64 s[26:27], -1, 0
	s_mov_b32 s24, s41
	v_mfma_f32_16x16x32_bf16 v[150:153], v[170:173], v[174:177], v[150:153]
	s_mov_b32 s23, s42
	s_mov_b64 s[28:29], -1
	s_and_b64 vcc, exec, s[26:27]
	v_mfma_f32_16x16x32_bf16 v[146:149], v[186:189], v[174:177], v[146:149]
	ds_read_b128 v[158:161], v0 offset:6144
	v_add_u32_e32 v174, v198, v181
	s_waitcnt lgkmcnt(2)
	v_mfma_f32_16x16x32_bf16 v[26:29], v[162:165], v[190:193], v[142:145]
	v_mfma_f32_16x16x32_bf16 v[138:141], v[166:169], v[190:193], v[138:141]
	v_mfma_f32_16x16x32_bf16 v[134:137], v[170:173], v[190:193], v[134:137]
	v_mfma_f32_16x16x32_bf16 v[130:133], v[186:189], v[190:193], v[130:133]
	ds_read_b128 v[142:145], v0 offset:8192
	s_waitcnt lgkmcnt(2)
	v_mfma_f32_16x16x32_bf16 v[22:25], v[162:165], v[194:197], v[126:129]
	v_mfma_f32_16x16x32_bf16 v[122:125], v[166:169], v[194:197], v[122:125]
	v_mfma_f32_16x16x32_bf16 v[118:121], v[170:173], v[194:197], v[118:121]
	v_mfma_f32_16x16x32_bf16 v[114:117], v[186:189], v[194:197], v[114:117]
	ds_read_b128 v[126:129], v0 offset:10240
	s_waitcnt lgkmcnt(2)
	v_mfma_f32_16x16x32_bf16 v[18:21], v[162:165], v[158:161], v[106:109]
	v_mfma_f32_16x16x32_bf16 v[102:105], v[166:169], v[158:161], v[102:105]
	v_mfma_f32_16x16x32_bf16 v[98:101], v[170:173], v[158:161], v[98:101]
	v_mfma_f32_16x16x32_bf16 v[94:97], v[186:189], v[158:161], v[94:97]
	ds_read_b128 v[106:109], v0 offset:12288
	ds_read_b128 v[158:161], v174 offset:32768
	s_waitcnt lgkmcnt(3)
	v_mfma_f32_16x16x32_bf16 v[14:17], v[162:165], v[142:145], v[86:89]
	v_mfma_f32_16x16x32_bf16 v[82:85], v[166:169], v[142:145], v[82:85]
	v_mfma_f32_16x16x32_bf16 v[78:81], v[170:173], v[142:145], v[78:81]
	v_mfma_f32_16x16x32_bf16 v[74:77], v[186:189], v[142:145], v[74:77]
	ds_read_b128 v[86:89], v0 offset:14336
	ds_read_b128 v[142:145], v174 offset:34816
	v_add_u32_e32 v0, v0, v181
	s_waitcnt lgkmcnt(4)
	v_mfma_f32_16x16x32_bf16 v[10:13], v[162:165], v[126:129], v[70:73]
	v_mfma_f32_16x16x32_bf16 v[66:69], v[166:169], v[126:129], v[66:69]
	v_mfma_f32_16x16x32_bf16 v[62:65], v[170:173], v[126:129], v[62:65]
	v_mfma_f32_16x16x32_bf16 v[58:61], v[186:189], v[126:129], v[58:61]
	ds_read_b128 v[70:73], v0 offset:0
	ds_read_b128 v[126:129], v174 offset:36864
	s_waitcnt lgkmcnt(5)
	v_mfma_f32_16x16x32_bf16 v[6:9], v[162:165], v[106:109], v[54:57]
	v_mfma_f32_16x16x32_bf16 v[50:53], v[166:169], v[106:109], v[50:53]
	v_mfma_f32_16x16x32_bf16 v[46:49], v[170:173], v[106:109], v[46:49]
	v_mfma_f32_16x16x32_bf16 v[42:45], v[186:189], v[106:109], v[42:45]
	ds_read_b128 v[106:109], v174 offset:38912
	ds_read_b128 v[54:57], v0 offset:2048
	s_waitcnt lgkmcnt(5)
	v_mfma_f32_16x16x32_bf16 v[2:5], v[162:165], v[86:89], v[38:41]
	v_mfma_f32_16x16x32_bf16 v[34:37], v[166:169], v[86:89], v[34:37]
	v_mfma_f32_16x16x32_bf16 v[38:41], v[170:173], v[86:89], v[90:93]
	v_mfma_f32_16x16x32_bf16 v[86:89], v[186:189], v[86:89], v[110:113]
	s_nop 1
	ds_read_b128 v[90:93], v0 offset:4096
	s_waitcnt lgkmcnt(4)
	v_mfma_f32_16x16x32_bf16 v[30:33], v[158:161], v[70:73], v[30:33]
	v_mfma_f32_16x16x32_bf16 v[110:113], v[142:145], v[70:73], v[154:157]
	s_waitcnt lgkmcnt(3)
	v_mfma_f32_16x16x32_bf16 v[150:153], v[126:129], v[70:73], v[150:153]
	s_waitcnt lgkmcnt(2)
	v_mfma_f32_16x16x32_bf16 v[70:73], v[106:109], v[70:73], v[146:149]
	s_nop 2
	ds_read_b128 v[146:149], v0 offset:6144
	s_waitcnt lgkmcnt(2)
	v_mfma_f32_16x16x32_bf16 v[26:29], v[158:161], v[54:57], v[26:29]
	v_mfma_f32_16x16x32_bf16 v[138:141], v[142:145], v[54:57], v[138:141]
	v_mfma_f32_16x16x32_bf16 v[134:137], v[126:129], v[54:57], v[134:137]
	v_mfma_f32_16x16x32_bf16 v[54:57], v[106:109], v[54:57], v[130:133]
	s_nop 2
	ds_read_b128 v[130:133], v0 offset:8192
	s_waitcnt lgkmcnt(2)
	v_mfma_f32_16x16x32_bf16 v[22:25], v[158:161], v[90:93], v[22:25]
	v_mfma_f32_16x16x32_bf16 v[122:125], v[142:145], v[90:93], v[122:125]
	v_mfma_f32_16x16x32_bf16 v[118:121], v[126:129], v[90:93], v[118:121]
	v_mfma_f32_16x16x32_bf16 v[90:93], v[106:109], v[90:93], v[114:117]
	s_nop 2
	ds_read_b128 v[114:117], v0 offset:10240
	s_waitcnt lgkmcnt(2)
	v_mfma_f32_16x16x32_bf16 v[18:21], v[158:161], v[146:149], v[18:21]
	v_mfma_f32_16x16x32_bf16 v[102:105], v[142:145], v[146:149], v[102:105]
	v_mfma_f32_16x16x32_bf16 v[98:101], v[126:129], v[146:149], v[98:101]
	v_mfma_f32_16x16x32_bf16 v[94:97], v[106:109], v[146:149], v[94:97]
	ds_read_b128 v[146:149], v0 offset:12288
	s_waitcnt lgkmcnt(2)
	v_mfma_f32_16x16x32_bf16 v[14:17], v[158:161], v[130:133], v[14:17]
	v_mfma_f32_16x16x32_bf16 v[82:85], v[142:145], v[130:133], v[82:85]
	v_mfma_f32_16x16x32_bf16 v[78:81], v[126:129], v[130:133], v[78:81]
	v_mfma_f32_16x16x32_bf16 v[74:77], v[106:109], v[130:133], v[74:77]
	ds_read_b128 v[130:133], v0 offset:14336
	v_or_b32_e32 v0, s3, v180
	v_add_u32_e32 v186, v0, v184
	s_waitcnt lgkmcnt(2)
	v_mfma_f32_16x16x32_bf16 v[10:13], v[158:161], v[114:117], v[10:13]
	s_waitcnt vmcnt(0) lgkmcnt(0)
	s_barrier
	v_mfma_f32_16x16x32_bf16 v[66:69], v[142:145], v[114:117], v[66:69]
	v_add_u32_e32 v0, v0, v183
	v_mfma_f32_16x16x32_bf16 v[62:65], v[126:129], v[114:117], v[62:65]
	v_mfma_f32_16x16x32_bf16 v[58:61], v[106:109], v[114:117], v[58:61]
	v_mfma_f32_16x16x32_bf16 v[6:9], v[158:161], v[146:149], v[6:9]
	v_mfma_f32_16x16x32_bf16 v[50:53], v[142:145], v[146:149], v[50:53]
	v_mfma_f32_16x16x32_bf16 v[46:49], v[126:129], v[146:149], v[46:49]
	v_mfma_f32_16x16x32_bf16 v[42:45], v[106:109], v[146:149], v[42:45]
	v_mfma_f32_16x16x32_bf16 v[2:5], v[158:161], v[130:133], v[2:5]
	v_mfma_f32_16x16x32_bf16 v[34:37], v[142:145], v[130:133], v[34:37]
	v_mfma_f32_16x16x32_bf16 v[38:41], v[126:129], v[130:133], v[38:41]
	v_mfma_f32_16x16x32_bf16 v[86:89], v[106:109], v[130:133], v[86:89]
	ds_read_b128 v[106:109], v186 offset:32768
	ds_read_b128 v[114:117], v186 offset:34816
	ds_read_b128 v[130:133], v186 offset:36864
	ds_read_b128 v[142:145], v186 offset:38912
	ds_read_b128 v[126:129], v0
	ds_read_b128 v[146:149], v0 offset:2048
	ds_read_b128 v[154:157], v0 offset:4096
	s_waitcnt lgkmcnt(2)
	v_mfma_f32_16x16x32_bf16 v[30:33], v[106:109], v[126:129], v[30:33]
	v_mfma_f32_16x16x32_bf16 v[110:113], v[114:117], v[126:129], v[110:113]
	v_mfma_f32_16x16x32_bf16 v[150:153], v[130:133], v[126:129], v[150:153]
	v_mfma_f32_16x16x32_bf16 v[70:73], v[142:145], v[126:129], v[70:73]
	ds_read_b128 v[126:129], v0 offset:6144
	s_waitcnt lgkmcnt(2)
	v_mfma_f32_16x16x32_bf16 v[26:29], v[106:109], v[146:149], v[26:29]
	v_mfma_f32_16x16x32_bf16 v[138:141], v[114:117], v[146:149], v[138:141]
	v_mfma_f32_16x16x32_bf16 v[134:137], v[130:133], v[146:149], v[134:137]
	v_mfma_f32_16x16x32_bf16 v[54:57], v[142:145], v[146:149], v[54:57]
	ds_read_b128 v[146:149], v0 offset:8192
	s_waitcnt lgkmcnt(2)
	v_mfma_f32_16x16x32_bf16 v[22:25], v[106:109], v[154:157], v[22:25]
	v_mfma_f32_16x16x32_bf16 v[158:161], v[114:117], v[154:157], v[122:125]
	v_mfma_f32_16x16x32_bf16 v[162:165], v[130:133], v[154:157], v[118:121]
	v_mfma_f32_16x16x32_bf16 v[154:157], v[142:145], v[154:157], v[90:93]
	s_nop 2
	ds_read_b128 v[90:93], v0 offset:10240
	s_waitcnt lgkmcnt(2)
	v_mfma_f32_16x16x32_bf16 v[18:21], v[106:109], v[126:129], v[18:21]
	v_mfma_f32_16x16x32_bf16 v[166:169], v[114:117], v[126:129], v[102:105]
	v_mfma_f32_16x16x32_bf16 v[170:173], v[130:133], v[126:129], v[98:101]
	v_mfma_f32_16x16x32_bf16 v[174:177], v[142:145], v[126:129], v[94:97]
	s_nop 1
	v_add_u32_e32 v98, v186, v181
	ds_read_b128 v[186:189], v98 offset:32768
	ds_read_b128 v[94:97], v0 offset:12288
	s_waitcnt lgkmcnt(3)
	v_mfma_f32_16x16x32_bf16 v[14:17], v[106:109], v[146:149], v[14:17]
	v_mfma_f32_16x16x32_bf16 v[190:193], v[114:117], v[146:149], v[82:85]
	v_mfma_f32_16x16x32_bf16 v[194:197], v[130:133], v[146:149], v[78:81]
	v_mfma_f32_16x16x32_bf16 v[146:149], v[142:145], v[146:149], v[74:77]
	ds_read_b128 v[198:201], v98 offset:34816
	s_nop 1
	ds_read_b128 v[74:77], v0 offset:14336
	v_add_u32_e32 v0, v0, v181
	s_waitcnt lgkmcnt(4)
	v_mfma_f32_16x16x32_bf16 v[10:13], v[106:109], v[90:93], v[10:13]
	v_mfma_f32_16x16x32_bf16 v[202:205], v[114:117], v[90:93], v[66:69]
	v_mfma_f32_16x16x32_bf16 v[206:209], v[130:133], v[90:93], v[62:65]
	v_mfma_f32_16x16x32_bf16 v[226:229], v[142:145], v[90:93], v[58:61]
	ds_read_b128 v[230:233], v98 offset:36864
	s_nop 1
	ds_read_b128 v[58:61], v0 offset:0
	s_waitcnt lgkmcnt(4)
	v_mfma_f32_16x16x32_bf16 v[6:9], v[106:109], v[94:97], v[6:9]
	v_mfma_f32_16x16x32_bf16 v[234:237], v[114:117], v[94:97], v[50:53]
	v_mfma_f32_16x16x32_bf16 v[238:241], v[130:133], v[94:97], v[46:49]
	v_mfma_f32_16x16x32_bf16 v[242:245], v[142:145], v[94:97], v[42:45]
	ds_read_b128 v[246:249], v98 offset:38912
	s_nop 1
	ds_read_b128 v[42:45], v0 offset:2048
	s_waitcnt lgkmcnt(4)
; #define ST_BF4(PTR, X0, X1, X2, X3) { u32x2 w_; w_[0] = pack2((X0), (X1)); w_[1] = pack2((X2), (X3)); *(u32x2*)(PTR) = w_; }
; template <int NT, int BM, int BN, bool PLAIN, int NSTAGE, bool EPI_LDS>
; __device__ __forceinline__ void gemm_tile(const Params& p, const GemmDesc& g, bf16_t* lds, const int tid) {
;     ...
;   if (EPI_LDS) {
;     constexpr int CST = BN + 16;
;     bf16_t* ct = lds;
;     const bool relu2 = (g.epi == E_RELU2);
; #pragma unroll
;     for (int mi = 0; mi < MI; ++mi)
; #pragma unroll
;       for (int ni = 0; ni < NI; ++ni) {
;         f32x4 v = acc[mi][ni];
;         if (relu2) {
; #pragma unroll
;           for (int j = 0; j < 4; ++j) { const float r = fmaxf(v[j], 0.f); v[j] = r * r; }
;         }
;         u32x2 w;
;         w[0] = pack2(v[0], v[1]);
;         w[1] = pack2(v[2], v[3]);
;         *(u32x2*)(ct + (wm * WTM + mi * 16 + fr) * CST + wn * WTN + ni * 16 + fq * 4) = w;
;       }
;     __syncthreads();
;     constexpr int PPR = BN / 8;
;     constexpr int NIT = BM * PPR / NT;
;     bf16_t* o = (bf16_t*)g.out;
;     const long ldo = (g.epi == E_PROJ) ? LDP : (g.epi == E_RELU2 ? 8192 : 2048);
;     const int gcol = COL_BG + g.auxi * 2048;
; #pragma unroll 4
;     for (int i = 0; i < NIT; ++i) {
;       const int id = tid + NT * i;
;       const int row = id / PPR, pc = id % PPR;
;       u32x4 v = *(const u32x4*)(ct + row * CST + pc * 8);
;       bf16_t* op = o + (long)(m0e + row) * ldo + n0e + pc * 8;
;     ...
;   switch (g.epi) {
;     case E_PROJ: {
;       bf16_t* o = (bf16_t*)g.out;
;       EPI_LOOP(ST_BF4(o + (long)row * LDP + col, v[0], v[1], v[2], v[3]))
	v_mfma_f32_16x16x32_bf16 v[2:5], v[106:109], v[74:77], v[2:5]
	v_mfma_f32_16x16x32_bf16 v[218:221], v[114:117], v[74:77], v[34:37]
	v_mfma_f32_16x16x32_bf16 v[130:133], v[130:133], v[74:77], v[38:41]
	v_mfma_f32_16x16x32_bf16 v[142:145], v[142:145], v[74:77], v[86:89]
	s_nop 0
	ds_read_b128 v[34:37], v0 offset:4096
	s_waitcnt lgkmcnt(3)
	v_mfma_f32_16x16x32_bf16 v[126:129], v[186:189], v[58:61], v[30:33]
	v_mfma_f32_16x16x32_bf16 v[122:125], v[198:201], v[58:61], v[110:113]
	v_mfma_f32_16x16x32_bf16 v[118:121], v[230:233], v[58:61], v[150:153]
	s_waitcnt lgkmcnt(2)
	v_mfma_f32_16x16x32_bf16 v[114:117], v[246:249], v[58:61], v[70:73]
	ds_read_b128 v[30:33], v0 offset:6144
	s_waitcnt lgkmcnt(2)
	v_mfma_f32_16x16x32_bf16 v[110:113], v[186:189], v[42:45], v[26:29]
	v_mfma_f32_16x16x32_bf16 v[106:109], v[198:201], v[42:45], v[138:141]
	v_mfma_f32_16x16x32_bf16 v[102:105], v[230:233], v[42:45], v[134:137]
	v_mfma_f32_16x16x32_bf16 v[98:101], v[246:249], v[42:45], v[54:57]
	ds_read_b128 v[26:29], v0 offset:8192
	s_waitcnt lgkmcnt(2)
	v_mfma_f32_16x16x32_bf16 v[94:97], v[186:189], v[34:37], v[22:25]
	v_mfma_f32_16x16x32_bf16 v[90:93], v[198:201], v[34:37], v[158:161]
	v_mfma_f32_16x16x32_bf16 v[86:89], v[230:233], v[34:37], v[162:165]
	v_mfma_f32_16x16x32_bf16 v[82:85], v[246:249], v[34:37], v[154:157]
	ds_read_b128 v[22:25], v0 offset:10240
	s_waitcnt lgkmcnt(2)
	v_mfma_f32_16x16x32_bf16 v[78:81], v[186:189], v[30:33], v[18:21]
	v_mfma_f32_16x16x32_bf16 v[74:77], v[198:201], v[30:33], v[166:169]
	v_mfma_f32_16x16x32_bf16 v[70:73], v[230:233], v[30:33], v[170:173]
	v_mfma_f32_16x16x32_bf16 v[66:69], v[246:249], v[30:33], v[174:177]
	ds_read_b128 v[18:21], v0 offset:12288
	s_waitcnt lgkmcnt(2)
	v_mfma_f32_16x16x32_bf16 v[62:65], v[186:189], v[26:29], v[14:17]
	v_mfma_f32_16x16x32_bf16 v[58:61], v[198:201], v[26:29], v[190:193]
	v_mfma_f32_16x16x32_bf16 v[54:57], v[230:233], v[26:29], v[194:197]
	v_mfma_f32_16x16x32_bf16 v[50:53], v[246:249], v[26:29], v[146:149]
	ds_read_b128 v[134:137], v0 offset:14336
	s_waitcnt lgkmcnt(0)
	s_barrier
	v_mfma_f32_16x16x32_bf16 v[46:49], v[186:189], v[22:25], v[10:13]
	v_mfma_f32_16x16x32_bf16 v[42:45], v[198:201], v[22:25], v[202:205]
	v_mfma_f32_16x16x32_bf16 v[38:41], v[230:233], v[22:25], v[206:209]
	v_mfma_f32_16x16x32_bf16 v[34:37], v[246:249], v[22:25], v[226:229]
	v_mfma_f32_16x16x32_bf16 v[30:33], v[186:189], v[18:21], v[6:9]
	v_mfma_f32_16x16x32_bf16 v[26:29], v[198:201], v[18:21], v[234:237]
	v_mfma_f32_16x16x32_bf16 v[22:25], v[230:233], v[18:21], v[238:241]
	v_mfma_f32_16x16x32_bf16 v[18:21], v[246:249], v[18:21], v[242:245]
	v_mfma_f32_16x16x32_bf16 v[14:17], v[186:189], v[134:137], v[2:5]
	v_mfma_f32_16x16x32_bf16 v[10:13], v[198:201], v[134:137], v[218:221]
	v_mfma_f32_16x16x32_bf16 v[2:5], v[230:233], v[134:137], v[130:133]
	v_mfma_f32_16x16x32_bf16 v[6:9], v[246:249], v[134:137], v[142:145]
	s_and_b32 s57, s56, 14
	s_cmp_eq_u32 s57, 6
	s_cbranch_scc1 .Lmy_stage
	s_cmp_lg_u32 s56, 0
	s_movk_i32 s60, 0x2880
	s_cselect_b32 s58, 0x800, s60
	s_cmp_eq_u32 s56, 9
	s_cselect_b32 s58, 0x2000, s58
	s_cbranch_scc1 .Lmy_directR
.Lmy_directP:
	v_and_b32_e32 v0, 63, v224
	v_lshrrev_b32_e32 v190, 6, v224
	v_and_b32_e32 v191, 15, v0
	v_lshrrev_b32_e32 v192, 4, v0
	v_lshrrev_b32_e32 v193, 2, v190
	v_and_b32_e32 v190, 3, v190
	v_lshl_or_b32 v191, v193, 7, v191
	s_lshl_b32 s57, s58, 1
	v_mul_lo_u32 v191, v191, s57
	v_lshl_add_u32 v191, v190, 7, v191
	v_and_b32_e32 v193, 1, v192
	v_lshl_add_u32 v191, v193, 5, v191
	v_lshrrev_b32_e32 v193, 1, v192
	v_lshl_add_u32 v191, v193, 4, v191
	s_mul_i32 s60, s23, s57
	s_lshl_b32 s61, s24, 1
	s_add_u32 s60, s60, s61
	s_add_u32 s64, s0, s60
	s_addc_u32 s65, s1, 0
	s_lshl_b32 s60, s57, 4
	v_cvt_pk_bf16_f32 v200, v126, v127
	v_cvt_pk_bf16_f32 v201, v128, v129
	v_cvt_pk_bf16_f32 v202, v122, v123
	v_cvt_pk_bf16_f32 v203, v124, v125
	v_cvt_pk_bf16_f32 v204, v118, v119
	v_cvt_pk_bf16_f32 v205, v120, v121
	v_cvt_pk_bf16_f32 v206, v114, v115
	v_cvt_pk_bf16_f32 v207, v116, v117
	v_permlane16_swap_b32_e32 v200, v202
	v_permlane16_swap_b32_e32 v201, v203
	global_store_dwordx4 v191, v[200:203], s[64:65]
	v_cvt_pk_bf16_f32 v208, v110, v111
	v_cvt_pk_bf16_f32 v209, v112, v113
	v_cvt_pk_bf16_f32 v210, v106, v107
	v_cvt_pk_bf16_f32 v211, v108, v109
	v_permlane16_swap_b32_e32 v204, v206
	v_permlane16_swap_b32_e32 v205, v207
	global_store_dwordx4 v191, v[204:207], s[64:65] offset:64
	s_add_u32 s64, s64, s60
	s_addc_u32 s65, s65, 0
	v_cvt_pk_bf16_f32 v228, v102, v103
	v_cvt_pk_bf16_f32 v229, v104, v105
	v_cvt_pk_bf16_f32 v230, v98, v99
	v_cvt_pk_bf16_f32 v231, v100, v101
	v_permlane16_swap_b32_e32 v208, v210
	v_permlane16_swap_b32_e32 v209, v211
	global_store_dwordx4 v191, v[208:211], s[64:65]
	v_cvt_pk_bf16_f32 v200, v94, v95
	v_cvt_pk_bf16_f32 v201, v96, v97
	v_cvt_pk_bf16_f32 v202, v90, v91
	v_cvt_pk_bf16_f32 v203, v92, v93
	v_permlane16_swap_b32_e32 v228, v230
	v_permlane16_swap_b32_e32 v229, v231
	global_store_dwordx4 v191, v[228:231], s[64:65] offset:64
	s_add_u32 s64, s64, s60
	s_addc_u32 s65, s65, 0
	v_cvt_pk_bf16_f32 v204, v86, v87
	v_cvt_pk_bf16_f32 v205, v88, v89
	v_cvt_pk_bf16_f32 v206, v82, v83
	v_cvt_pk_bf16_f32 v207, v84, v85
	v_permlane16_swap_b32_e32 v200, v202
	v_permlane16_swap_b32_e32 v201, v203
	global_store_dwordx4 v191, v[200:203], s[64:65]
	v_cvt_pk_bf16_f32 v208, v78, v79
	v_cvt_pk_bf16_f32 v209, v80, v81
	v_cvt_pk_bf16_f32 v210, v74, v75
	v_cvt_pk_bf16_f32 v211, v76, v77
	v_permlane16_swap_b32_e32 v204, v206
	v_permlane16_swap_b32_e32 v205, v207
	global_store_dwordx4 v191, v[204:207], s[64:65] offset:64
	s_add_u32 s64, s64, s60
	s_addc_u32 s65, s65, 0
; #define ST_BF4(PTR, X0, X1, X2, X3) { u32x2 w_; w_[0] = pack2((X0), (X1)); w_[1] = pack2((X2), (X3)); *(u32x2*)(PTR) = w_; }
; template <int NT, int BM, int BN, bool PLAIN, int NSTAGE, bool EPI_LDS>
; __device__ __forceinline__ void gemm_tile(const Params& p, const GemmDesc& g, bf16_t* lds, const int tid) {
;     ...
;   switch (g.epi) {
;     case E_PROJ: {
;       bf16_t* o = (bf16_t*)g.out;
;       EPI_LOOP(ST_BF4(o + (long)row * LDP + col, v[0], v[1], v[2], v[3]))
;     ...
;     case E_RELU2: {
;       bf16_t* o = (bf16_t*)g.out;
;       EPI_LOOP(
;         const float r0_ = fmaxf(v[0], 0.f), r1_ = fmaxf(v[1], 0.f), r2_ = fmaxf(v[2], 0.f), r3_ = fmaxf(v[3], 0.f);
;         ST_BF4(o + (long)row * 8192 + col, r0_ * r0_, r1_ * r1_, r2_ * r2_, r3_ * r3_))
;     } break;
	v_cvt_pk_bf16_f32 v228, v70, v71
	v_cvt_pk_bf16_f32 v229, v72, v73
	v_cvt_pk_bf16_f32 v230, v66, v67
	v_cvt_pk_bf16_f32 v231, v68, v69
	v_permlane16_swap_b32_e32 v208, v210
	v_permlane16_swap_b32_e32 v209, v211
	global_store_dwordx4 v191, v[208:211], s[64:65]
	v_cvt_pk_bf16_f32 v200, v62, v63
	v_cvt_pk_bf16_f32 v201, v64, v65
	v_cvt_pk_bf16_f32 v202, v58, v59
	v_cvt_pk_bf16_f32 v203, v60, v61
	v_permlane16_swap_b32_e32 v228, v230
	v_permlane16_swap_b32_e32 v229, v231
	global_store_dwordx4 v191, v[228:231], s[64:65] offset:64
	s_add_u32 s64, s64, s60
	s_addc_u32 s65, s65, 0
	v_cvt_pk_bf16_f32 v204, v54, v55
	v_cvt_pk_bf16_f32 v205, v56, v57
	v_cvt_pk_bf16_f32 v206, v50, v51
	v_cvt_pk_bf16_f32 v207, v52, v53
	v_permlane16_swap_b32_e32 v200, v202
	v_permlane16_swap_b32_e32 v201, v203
	global_store_dwordx4 v191, v[200:203], s[64:65]
	v_cvt_pk_bf16_f32 v208, v46, v47
	v_cvt_pk_bf16_f32 v209, v48, v49
	v_cvt_pk_bf16_f32 v210, v42, v43
	v_cvt_pk_bf16_f32 v211, v44, v45
	v_permlane16_swap_b32_e32 v204, v206
	v_permlane16_swap_b32_e32 v205, v207
	global_store_dwordx4 v191, v[204:207], s[64:65] offset:64
	s_add_u32 s64, s64, s60
	s_addc_u32 s65, s65, 0
	v_cvt_pk_bf16_f32 v228, v38, v39
	v_cvt_pk_bf16_f32 v229, v40, v41
	v_cvt_pk_bf16_f32 v230, v34, v35
	v_cvt_pk_bf16_f32 v231, v36, v37
	v_permlane16_swap_b32_e32 v208, v210
	v_permlane16_swap_b32_e32 v209, v211
	global_store_dwordx4 v191, v[208:211], s[64:65]
	v_cvt_pk_bf16_f32 v200, v30, v31
	v_cvt_pk_bf16_f32 v201, v32, v33
	v_cvt_pk_bf16_f32 v202, v26, v27
	v_cvt_pk_bf16_f32 v203, v28, v29
	v_permlane16_swap_b32_e32 v228, v230
	v_permlane16_swap_b32_e32 v229, v231
	global_store_dwordx4 v191, v[228:231], s[64:65] offset:64
	s_add_u32 s64, s64, s60
	s_addc_u32 s65, s65, 0
	v_cvt_pk_bf16_f32 v204, v22, v23
	v_cvt_pk_bf16_f32 v205, v24, v25
	v_cvt_pk_bf16_f32 v206, v18, v19
	v_cvt_pk_bf16_f32 v207, v20, v21
	v_permlane16_swap_b32_e32 v200, v202
	v_permlane16_swap_b32_e32 v201, v203
	global_store_dwordx4 v191, v[200:203], s[64:65]
	v_cvt_pk_bf16_f32 v208, v14, v15
	v_cvt_pk_bf16_f32 v209, v16, v17
	v_cvt_pk_bf16_f32 v210, v10, v11
	v_cvt_pk_bf16_f32 v211, v12, v13
	v_permlane16_swap_b32_e32 v204, v206
	v_permlane16_swap_b32_e32 v205, v207
	global_store_dwordx4 v191, v[204:207], s[64:65] offset:64
	s_add_u32 s64, s64, s60
	s_addc_u32 s65, s65, 0
	v_cvt_pk_bf16_f32 v228, v2, v3
	v_cvt_pk_bf16_f32 v229, v4, v5
	v_cvt_pk_bf16_f32 v230, v6, v7
	v_cvt_pk_bf16_f32 v231, v8, v9
	v_permlane16_swap_b32_e32 v208, v210
	v_permlane16_swap_b32_e32 v209, v211
	global_store_dwordx4 v191, v[208:211], s[64:65]
	s_nop 1
	v_permlane16_swap_b32_e32 v228, v230
	v_permlane16_swap_b32_e32 v229, v231
	global_store_dwordx4 v191, v[228:231], s[64:65] offset:64
	s_branch .LBB0_888
.Lmy_directR:
	v_and_b32_e32 v0, 63, v224
	v_lshrrev_b32_e32 v190, 6, v224
	v_and_b32_e32 v191, 15, v0
	v_lshrrev_b32_e32 v192, 4, v0
	v_lshrrev_b32_e32 v193, 2, v190
	v_and_b32_e32 v190, 3, v190
	v_lshl_or_b32 v191, v193, 7, v191
	s_lshl_b32 s57, s58, 1
	v_mul_lo_u32 v191, v191, s57
	v_lshl_add_u32 v191, v190, 7, v191
	v_and_b32_e32 v193, 1, v192
	v_lshl_add_u32 v191, v193, 5, v191
	v_lshrrev_b32_e32 v193, 1, v192
	v_lshl_add_u32 v191, v193, 4, v191
	s_mul_i32 s60, s23, s57
	s_lshl_b32 s61, s24, 1
	s_add_u32 s60, s60, s61
	s_add_u32 s64, s0, s60
	s_addc_u32 s65, s1, 0
	s_lshl_b32 s60, s57, 4
	v_max_f32_e32 v0, v126, v126
	v_max_f32_e32 v126, 0, v0
	v_mul_f32_e32 v126, v126, v126
	v_max_f32_e32 v0, v127, v127
	v_max_f32_e32 v127, 0, v0
	v_mul_f32_e32 v127, v127, v127
	v_max_f32_e32 v0, v128, v128
	v_max_f32_e32 v128, 0, v0
	v_mul_f32_e32 v128, v128, v128
	v_max_f32_e32 v0, v129, v129
	v_max_f32_e32 v129, 0, v0
	v_mul_f32_e32 v129, v129, v129
	v_max_f32_e32 v0, v122, v122
	v_max_f32_e32 v122, 0, v0
	v_mul_f32_e32 v122, v122, v122
	v_max_f32_e32 v0, v123, v123
	v_max_f32_e32 v123, 0, v0
	v_mul_f32_e32 v123, v123, v123
	v_max_f32_e32 v0, v124, v124
	v_max_f32_e32 v124, 0, v0
	v_mul_f32_e32 v124, v124, v124
	v_max_f32_e32 v0, v125, v125
	v_max_f32_e32 v125, 0, v0
	v_mul_f32_e32 v125, v125, v125
	v_cvt_pk_bf16_f32 v200, v126, v127
	v_cvt_pk_bf16_f32 v201, v128, v129
	v_cvt_pk_bf16_f32 v202, v122, v123
	v_cvt_pk_bf16_f32 v203, v124, v125
	v_max_f32_e32 v0, v118, v118
	v_max_f32_e32 v118, 0, v0
	v_mul_f32_e32 v118, v118, v118
	v_max_f32_e32 v0, v119, v119
	v_max_f32_e32 v119, 0, v0
	v_mul_f32_e32 v119, v119, v119
	v_max_f32_e32 v0, v120, v120
	v_max_f32_e32 v120, 0, v0
	v_mul_f32_e32 v120, v120, v120
	v_max_f32_e32 v0, v121, v121
	v_max_f32_e32 v121, 0, v0
	v_mul_f32_e32 v121, v121, v121
	v_max_f32_e32 v0, v114, v114
	v_max_f32_e32 v114, 0, v0
	v_mul_f32_e32 v114, v114, v114
	v_max_f32_e32 v0, v115, v115
	v_max_f32_e32 v115, 0, v0
	v_mul_f32_e32 v115, v115, v115
	v_max_f32_e32 v0, v116, v116
	v_max_f32_e32 v116, 0, v0
	v_mul_f32_e32 v116, v116, v116
	v_max_f32_e32 v0, v117, v117
	v_max_f32_e32 v117, 0, v0
	v_mul_f32_e32 v117, v117, v117
	v_cvt_pk_bf16_f32 v204, v118, v119
	v_cvt_pk_bf16_f32 v205, v120, v121
	v_cvt_pk_bf16_f32 v206, v114, v115
	v_cvt_pk_bf16_f32 v207, v116, v117
	v_permlane16_swap_b32_e32 v200, v202
	v_permlane16_swap_b32_e32 v201, v203
	global_store_dwordx4 v191, v[200:203], s[64:65]
	v_max_f32_e32 v0, v110, v110
	v_max_f32_e32 v110, 0, v0
	v_mul_f32_e32 v110, v110, v110
	v_max_f32_e32 v0, v111, v111
	v_max_f32_e32 v111, 0, v0
	v_mul_f32_e32 v111, v111, v111
	v_max_f32_e32 v0, v112, v112
	v_max_f32_e32 v112, 0, v0
	v_mul_f32_e32 v112, v112, v112
	v_max_f32_e32 v0, v113, v113
	v_max_f32_e32 v113, 0, v0
	v_mul_f32_e32 v113, v113, v113
	v_max_f32_e32 v0, v106, v106
	v_max_f32_e32 v106, 0, v0
	v_mul_f32_e32 v106, v106, v106
	v_max_f32_e32 v0, v107, v107
; #define ST_BF4(PTR, X0, X1, X2, X3) { u32x2 w_; w_[0] = pack2((X0), (X1)); w_[1] = pack2((X2), (X3)); *(u32x2*)(PTR) = w_; }
; template <int NT, int BM, int BN, bool PLAIN, int NSTAGE, bool EPI_LDS>
; __device__ __forceinline__ void gemm_tile(const Params& p, const GemmDesc& g, bf16_t* lds, const int tid) {
;     ...
;     case E_RELU2: {
;       bf16_t* o = (bf16_t*)g.out;
;       EPI_LOOP(
;         const float r0_ = fmaxf(v[0], 0.f), r1_ = fmaxf(v[1], 0.f), r2_ = fmaxf(v[2], 0.f), r3_ = fmaxf(v[3], 0.f);
;         ST_BF4(o + (long)row * 8192 + col, r0_ * r0_, r1_ * r1_, r2_ * r2_, r3_ * r3_))
;     } break;
	v_max_f32_e32 v107, 0, v0
	v_mul_f32_e32 v107, v107, v107
	v_max_f32_e32 v0, v108, v108
	v_max_f32_e32 v108, 0, v0
	v_mul_f32_e32 v108, v108, v108
	v_max_f32_e32 v0, v109, v109
	v_max_f32_e32 v109, 0, v0
	v_mul_f32_e32 v109, v109, v109
	v_cvt_pk_bf16_f32 v208, v110, v111
	v_cvt_pk_bf16_f32 v209, v112, v113
	v_cvt_pk_bf16_f32 v210, v106, v107
	v_cvt_pk_bf16_f32 v211, v108, v109
	v_permlane16_swap_b32_e32 v204, v206
	v_permlane16_swap_b32_e32 v205, v207
	global_store_dwordx4 v191, v[204:207], s[64:65] offset:64
	s_add_u32 s64, s64, s60
	s_addc_u32 s65, s65, 0
	v_max_f32_e32 v0, v102, v102
	v_max_f32_e32 v102, 0, v0
	v_mul_f32_e32 v102, v102, v102
	v_max_f32_e32 v0, v103, v103
	v_max_f32_e32 v103, 0, v0
	v_mul_f32_e32 v103, v103, v103
	v_max_f32_e32 v0, v104, v104
	v_max_f32_e32 v104, 0, v0
	v_mul_f32_e32 v104, v104, v104
	v_max_f32_e32 v0, v105, v105
	v_max_f32_e32 v105, 0, v0
	v_mul_f32_e32 v105, v105, v105
	v_max_f32_e32 v0, v98, v98
	v_max_f32_e32 v98, 0, v0
	v_mul_f32_e32 v98, v98, v98
	v_max_f32_e32 v0, v99, v99
	v_max_f32_e32 v99, 0, v0
	v_mul_f32_e32 v99, v99, v99
	v_max_f32_e32 v0, v100, v100
	v_max_f32_e32 v100, 0, v0
	v_mul_f32_e32 v100, v100, v100
	v_max_f32_e32 v0, v101, v101
	v_max_f32_e32 v101, 0, v0
	v_mul_f32_e32 v101, v101, v101
	v_cvt_pk_bf16_f32 v228, v102, v103
	v_cvt_pk_bf16_f32 v229, v104, v105
	v_cvt_pk_bf16_f32 v230, v98, v99
	v_cvt_pk_bf16_f32 v231, v100, v101
	v_permlane16_swap_b32_e32 v208, v210
	v_permlane16_swap_b32_e32 v209, v211
	global_store_dwordx4 v191, v[208:211], s[64:65]
	v_max_f32_e32 v0, v94, v94
	v_max_f32_e32 v94, 0, v0
	v_mul_f32_e32 v94, v94, v94
	v_max_f32_e32 v0, v95, v95
	v_max_f32_e32 v95, 0, v0
	v_mul_f32_e32 v95, v95, v95
	v_max_f32_e32 v0, v96, v96
	v_max_f32_e32 v96, 0, v0
	v_mul_f32_e32 v96, v96, v96
	v_max_f32_e32 v0, v97, v97
	v_max_f32_e32 v97, 0, v0
	v_mul_f32_e32 v97, v97, v97
	v_max_f32_e32 v0, v90, v90
	v_max_f32_e32 v90, 0, v0
	v_mul_f32_e32 v90, v90, v90
	v_max_f32_e32 v0, v91, v91
	v_max_f32_e32 v91, 0, v0
	v_mul_f32_e32 v91, v91, v91
	v_max_f32_e32 v0, v92, v92
	v_max_f32_e32 v92, 0, v0
	v_mul_f32_e32 v92, v92, v92
	v_max_f32_e32 v0, v93, v93
	v_max_f32_e32 v93, 0, v0
	v_mul_f32_e32 v93, v93, v93
	v_cvt_pk_bf16_f32 v200, v94, v95
	v_cvt_pk_bf16_f32 v201, v96, v97
	v_cvt_pk_bf16_f32 v202, v90, v91
	v_cvt_pk_bf16_f32 v203, v92, v93
	v_permlane16_swap_b32_e32 v228, v230
	v_permlane16_swap_b32_e32 v229, v231
	global_store_dwordx4 v191, v[228:231], s[64:65] offset:64
	s_add_u32 s64, s64, s60
	s_addc_u32 s65, s65, 0
	v_max_f32_e32 v0, v86, v86
	v_max_f32_e32 v86, 0, v0
	v_mul_f32_e32 v86, v86, v86
	v_max_f32_e32 v0, v87, v87
	v_max_f32_e32 v87, 0, v0
	v_mul_f32_e32 v87, v87, v87
	v_max_f32_e32 v0, v88, v88
	v_max_f32_e32 v88, 0, v0
	v_mul_f32_e32 v88, v88, v88
	v_max_f32_e32 v0, v89, v89
	v_max_f32_e32 v89, 0, v0
	v_mul_f32_e32 v89, v89, v89
	v_max_f32_e32 v0, v82, v82
	v_max_f32_e32 v82, 0, v0
	v_mul_f32_e32 v82, v82, v82
	v_max_f32_e32 v0, v83, v83
	v_max_f32_e32 v83, 0, v0
	v_mul_f32_e32 v83, v83, v83
	v_max_f32_e32 v0, v84, v84
	v_max_f32_e32 v84, 0, v0
	v_mul_f32_e32 v84, v84, v84
	v_max_f32_e32 v0, v85, v85
	v_max_f32_e32 v85, 0, v0
	v_mul_f32_e32 v85, v85, v85
	v_cvt_pk_bf16_f32 v204, v86, v87
	v_cvt_pk_bf16_f32 v205, v88, v89
	v_cvt_pk_bf16_f32 v206, v82, v83
	v_cvt_pk_bf16_f32 v207, v84, v85
	v_permlane16_swap_b32_e32 v200, v202
	v_permlane16_swap_b32_e32 v201, v203
	global_store_dwordx4 v191, v[200:203], s[64:65]
	v_max_f32_e32 v0, v78, v78
	v_max_f32_e32 v78, 0, v0
	v_mul_f32_e32 v78, v78, v78
	v_max_f32_e32 v0, v79, v79
	v_max_f32_e32 v79, 0, v0
	v_mul_f32_e32 v79, v79, v79
	v_max_f32_e32 v0, v80, v80
	v_max_f32_e32 v80, 0, v0
	v_mul_f32_e32 v80, v80, v80
	v_max_f32_e32 v0, v81, v81
	v_max_f32_e32 v81, 0, v0
	v_mul_f32_e32 v81, v81, v81
	v_max_f32_e32 v0, v74, v74
	v_max_f32_e32 v74, 0, v0
	v_mul_f32_e32 v74, v74, v74
	v_max_f32_e32 v0, v75, v75
	v_max_f32_e32 v75, 0, v0
	v_mul_f32_e32 v75, v75, v75
	v_max_f32_e32 v0, v76, v76
	v_max_f32_e32 v76, 0, v0
	v_mul_f32_e32 v76, v76, v76
	v_max_f32_e32 v0, v77, v77
	v_max_f32_e32 v77, 0, v0
	v_mul_f32_e32 v77, v77, v77
	v_cvt_pk_bf16_f32 v208, v78, v79
	v_cvt_pk_bf16_f32 v209, v80, v81
	v_cvt_pk_bf16_f32 v210, v74, v75
	v_cvt_pk_bf16_f32 v211, v76, v77
	v_permlane16_swap_b32_e32 v204, v206
	v_permlane16_swap_b32_e32 v205, v207
	global_store_dwordx4 v191, v[204:207], s[64:65] offset:64
	s_add_u32 s64, s64, s60
	s_addc_u32 s65, s65, 0
	v_max_f32_e32 v0, v70, v70
	v_max_f32_e32 v70, 0, v0
	v_mul_f32_e32 v70, v70, v70
	v_max_f32_e32 v0, v71, v71
	v_max_f32_e32 v71, 0, v0
	v_mul_f32_e32 v71, v71, v71
	v_max_f32_e32 v0, v72, v72
	v_max_f32_e32 v72, 0, v0
	v_mul_f32_e32 v72, v72, v72
	v_max_f32_e32 v0, v73, v73
	v_max_f32_e32 v73, 0, v0
	v_mul_f32_e32 v73, v73, v73
	v_max_f32_e32 v0, v66, v66
	v_max_f32_e32 v66, 0, v0
	v_mul_f32_e32 v66, v66, v66
	v_max_f32_e32 v0, v67, v67
	v_max_f32_e32 v67, 0, v0
	v_mul_f32_e32 v67, v67, v67
	v_max_f32_e32 v0, v68, v68
	v_max_f32_e32 v68, 0, v0
	v_mul_f32_e32 v68, v68, v68
	v_max_f32_e32 v0, v69, v69
	v_max_f32_e32 v69, 0, v0
	v_mul_f32_e32 v69, v69, v69
	v_cvt_pk_bf16_f32 v228, v70, v71
	v_cvt_pk_bf16_f32 v229, v72, v73
	v_cvt_pk_bf16_f32 v230, v66, v67
	v_cvt_pk_bf16_f32 v231, v68, v69
	v_permlane16_swap_b32_e32 v208, v210
	v_permlane16_swap_b32_e32 v209, v211
	global_store_dwordx4 v191, v[208:211], s[64:65]
	v_max_f32_e32 v0, v62, v62
	v_max_f32_e32 v62, 0, v0
	v_mul_f32_e32 v62, v62, v62
	v_max_f32_e32 v0, v63, v63
	v_max_f32_e32 v63, 0, v0
	v_mul_f32_e32 v63, v63, v63
	v_max_f32_e32 v0, v64, v64
	v_max_f32_e32 v64, 0, v0
	v_mul_f32_e32 v64, v64, v64
	v_max_f32_e32 v0, v65, v65
; #define ST_BF4(PTR, X0, X1, X2, X3) { u32x2 w_; w_[0] = pack2((X0), (X1)); w_[1] = pack2((X2), (X3)); *(u32x2*)(PTR) = w_; }
; template <int NT, int BM, int BN, bool PLAIN, int NSTAGE, bool EPI_LDS>
; __device__ __forceinline__ void gemm_tile(const Params& p, const GemmDesc& g, bf16_t* lds, const int tid) {
;     ...
;     case E_RELU2: {
;       bf16_t* o = (bf16_t*)g.out;
;       EPI_LOOP(
;         const float r0_ = fmaxf(v[0], 0.f), r1_ = fmaxf(v[1], 0.f), r2_ = fmaxf(v[2], 0.f), r3_ = fmaxf(v[3], 0.f);
;         ST_BF4(o + (long)row * 8192 + col, r0_ * r0_, r1_ * r1_, r2_ * r2_, r3_ * r3_))
;     } break;
	v_max_f32_e32 v65, 0, v0
	v_mul_f32_e32 v65, v65, v65
	v_max_f32_e32 v0, v58, v58
	v_max_f32_e32 v58, 0, v0
	v_mul_f32_e32 v58, v58, v58
	v_max_f32_e32 v0, v59, v59
	v_max_f32_e32 v59, 0, v0
	v_mul_f32_e32 v59, v59, v59
	v_max_f32_e32 v0, v60, v60
	v_max_f32_e32 v60, 0, v0
	v_mul_f32_e32 v60, v60, v60
	v_max_f32_e32 v0, v61, v61
	v_max_f32_e32 v61, 0, v0
	v_mul_f32_e32 v61, v61, v61
	v_cvt_pk_bf16_f32 v200, v62, v63
	v_cvt_pk_bf16_f32 v201, v64, v65
	v_cvt_pk_bf16_f32 v202, v58, v59
	v_cvt_pk_bf16_f32 v203, v60, v61
	v_permlane16_swap_b32_e32 v228, v230
	v_permlane16_swap_b32_e32 v229, v231
	global_store_dwordx4 v191, v[228:231], s[64:65] offset:64
	s_add_u32 s64, s64, s60
	s_addc_u32 s65, s65, 0
	v_max_f32_e32 v0, v54, v54
	v_max_f32_e32 v54, 0, v0
	v_mul_f32_e32 v54, v54, v54
	v_max_f32_e32 v0, v55, v55
	v_max_f32_e32 v55, 0, v0
	v_mul_f32_e32 v55, v55, v55
	v_max_f32_e32 v0, v56, v56
	v_max_f32_e32 v56, 0, v0
	v_mul_f32_e32 v56, v56, v56
	v_max_f32_e32 v0, v57, v57
	v_max_f32_e32 v57, 0, v0
	v_mul_f32_e32 v57, v57, v57
	v_max_f32_e32 v0, v50, v50
	v_max_f32_e32 v50, 0, v0
	v_mul_f32_e32 v50, v50, v50
	v_max_f32_e32 v0, v51, v51
	v_max_f32_e32 v51, 0, v0
	v_mul_f32_e32 v51, v51, v51
	v_max_f32_e32 v0, v52, v52
	v_max_f32_e32 v52, 0, v0
	v_mul_f32_e32 v52, v52, v52
	v_max_f32_e32 v0, v53, v53
	v_max_f32_e32 v53, 0, v0
	v_mul_f32_e32 v53, v53, v53
	v_cvt_pk_bf16_f32 v204, v54, v55
	v_cvt_pk_bf16_f32 v205, v56, v57
	v_cvt_pk_bf16_f32 v206, v50, v51
	v_cvt_pk_bf16_f32 v207, v52, v53
	v_permlane16_swap_b32_e32 v200, v202
	v_permlane16_swap_b32_e32 v201, v203
	global_store_dwordx4 v191, v[200:203], s[64:65]
	v_max_f32_e32 v0, v46, v46
	v_max_f32_e32 v46, 0, v0
	v_mul_f32_e32 v46, v46, v46
	v_max_f32_e32 v0, v47, v47
	v_max_f32_e32 v47, 0, v0
	v_mul_f32_e32 v47, v47, v47
	v_max_f32_e32 v0, v48, v48
	v_max_f32_e32 v48, 0, v0
	v_mul_f32_e32 v48, v48, v48
	v_max_f32_e32 v0, v49, v49
	v_max_f32_e32 v49, 0, v0
	v_mul_f32_e32 v49, v49, v49
	v_max_f32_e32 v0, v42, v42
	v_max_f32_e32 v42, 0, v0
	v_mul_f32_e32 v42, v42, v42
	v_max_f32_e32 v0, v43, v43
	v_max_f32_e32 v43, 0, v0
	v_mul_f32_e32 v43, v43, v43
	v_max_f32_e32 v0, v44, v44
	v_max_f32_e32 v44, 0, v0
	v_mul_f32_e32 v44, v44, v44
	v_max_f32_e32 v0, v45, v45
	v_max_f32_e32 v45, 0, v0
	v_mul_f32_e32 v45, v45, v45
	v_cvt_pk_bf16_f32 v208, v46, v47
	v_cvt_pk_bf16_f32 v209, v48, v49
	v_cvt_pk_bf16_f32 v210, v42, v43
	v_cvt_pk_bf16_f32 v211, v44, v45
	v_permlane16_swap_b32_e32 v204, v206
	v_permlane16_swap_b32_e32 v205, v207
	global_store_dwordx4 v191, v[204:207], s[64:65] offset:64
	s_add_u32 s64, s64, s60
	s_addc_u32 s65, s65, 0
	v_max_f32_e32 v0, v38, v38
	v_max_f32_e32 v38, 0, v0
	v_mul_f32_e32 v38, v38, v38
	v_max_f32_e32 v0, v39, v39
	v_max_f32_e32 v39, 0, v0
	v_mul_f32_e32 v39, v39, v39
	v_max_f32_e32 v0, v40, v40
	v_max_f32_e32 v40, 0, v0
	v_mul_f32_e32 v40, v40, v40
	v_max_f32_e32 v0, v41, v41
	v_max_f32_e32 v41, 0, v0
	v_mul_f32_e32 v41, v41, v41
	v_max_f32_e32 v0, v34, v34
	v_max_f32_e32 v34, 0, v0
	v_mul_f32_e32 v34, v34, v34
	v_max_f32_e32 v0, v35, v35
	v_max_f32_e32 v35, 0, v0
	v_mul_f32_e32 v35, v35, v35
	v_max_f32_e32 v0, v36, v36
	v_max_f32_e32 v36, 0, v0
	v_mul_f32_e32 v36, v36, v36
	v_max_f32_e32 v0, v37, v37
	v_max_f32_e32 v37, 0, v0
	v_mul_f32_e32 v37, v37, v37
	v_cvt_pk_bf16_f32 v228, v38, v39
	v_cvt_pk_bf16_f32 v229, v40, v41
	v_cvt_pk_bf16_f32 v230, v34, v35
	v_cvt_pk_bf16_f32 v231, v36, v37
	v_permlane16_swap_b32_e32 v208, v210
	v_permlane16_swap_b32_e32 v209, v211
	global_store_dwordx4 v191, v[208:211], s[64:65]
	v_max_f32_e32 v0, v30, v30
	v_max_f32_e32 v30, 0, v0
	v_mul_f32_e32 v30, v30, v30
	v_max_f32_e32 v0, v31, v31
	v_max_f32_e32 v31, 0, v0
	v_mul_f32_e32 v31, v31, v31
	v_max_f32_e32 v0, v32, v32
	v_max_f32_e32 v32, 0, v0
	v_mul_f32_e32 v32, v32, v32
; #define ST_BF4(PTR, X0, X1, X2, X3) { u32x2 w_; w_[0] = pack2((X0), (X1)); w_[1] = pack2((X2), (X3)); *(u32x2*)(PTR) = w_; }
; template <int NT, int BM, int BN, bool PLAIN, int NSTAGE, bool EPI_LDS>
; __device__ __forceinline__ void gemm_tile(const Params& p, const GemmDesc& g, bf16_t* lds, const int tid) {
;     ...
;   if (EPI_LDS) {
;     constexpr int CST = BN + 16;
;     bf16_t* ct = lds;
;     const bool relu2 = (g.epi == E_RELU2);
; #pragma unroll
;     for (int mi = 0; mi < MI; ++mi)
; #pragma unroll
;       for (int ni = 0; ni < NI; ++ni) {
;         f32x4 v = acc[mi][ni];
;         if (relu2) {
; #pragma unroll
;           for (int j = 0; j < 4; ++j) { const float r = fmaxf(v[j], 0.f); v[j] = r * r; }
;         }
;         u32x2 w;
;         w[0] = pack2(v[0], v[1]);
;         w[1] = pack2(v[2], v[3]);
;         *(u32x2*)(ct + (wm * WTM + mi * 16 + fr) * CST + wn * WTN + ni * 16 + fq * 4) = w;
;       }
;     __syncthreads();
;     ...
;     case E_RELU2: {
;       bf16_t* o = (bf16_t*)g.out;
;       EPI_LOOP(
;         const float r0_ = fmaxf(v[0], 0.f), r1_ = fmaxf(v[1], 0.f), r2_ = fmaxf(v[2], 0.f), r3_ = fmaxf(v[3], 0.f);
;         ST_BF4(o + (long)row * 8192 + col, r0_ * r0_, r1_ * r1_, r2_ * r2_, r3_ * r3_))
;     } break;
	v_max_f32_e32 v0, v33, v33
	v_max_f32_e32 v33, 0, v0
	v_mul_f32_e32 v33, v33, v33
	v_max_f32_e32 v0, v26, v26
	v_max_f32_e32 v26, 0, v0
	v_mul_f32_e32 v26, v26, v26
	v_max_f32_e32 v0, v27, v27
	v_max_f32_e32 v27, 0, v0
	v_mul_f32_e32 v27, v27, v27
	v_max_f32_e32 v0, v28, v28
	v_max_f32_e32 v28, 0, v0
	v_mul_f32_e32 v28, v28, v28
	v_max_f32_e32 v0, v29, v29
	v_max_f32_e32 v29, 0, v0
	v_mul_f32_e32 v29, v29, v29
	v_cvt_pk_bf16_f32 v200, v30, v31
	v_cvt_pk_bf16_f32 v201, v32, v33
	v_cvt_pk_bf16_f32 v202, v26, v27
	v_cvt_pk_bf16_f32 v203, v28, v29
	v_permlane16_swap_b32_e32 v228, v230
	v_permlane16_swap_b32_e32 v229, v231
	global_store_dwordx4 v191, v[228:231], s[64:65] offset:64
	s_add_u32 s64, s64, s60
	s_addc_u32 s65, s65, 0
	v_max_f32_e32 v0, v22, v22
	v_max_f32_e32 v22, 0, v0
	v_mul_f32_e32 v22, v22, v22
	v_max_f32_e32 v0, v23, v23
	v_max_f32_e32 v23, 0, v0
	v_mul_f32_e32 v23, v23, v23
	v_max_f32_e32 v0, v24, v24
	v_max_f32_e32 v24, 0, v0
	v_mul_f32_e32 v24, v24, v24
	v_max_f32_e32 v0, v25, v25
	v_max_f32_e32 v25, 0, v0
	v_mul_f32_e32 v25, v25, v25
	v_max_f32_e32 v0, v18, v18
	v_max_f32_e32 v18, 0, v0
	v_mul_f32_e32 v18, v18, v18
	v_max_f32_e32 v0, v19, v19
	v_max_f32_e32 v19, 0, v0
	v_mul_f32_e32 v19, v19, v19
	v_max_f32_e32 v0, v20, v20
	v_max_f32_e32 v20, 0, v0
	v_mul_f32_e32 v20, v20, v20
	v_max_f32_e32 v0, v21, v21
	v_max_f32_e32 v21, 0, v0
	v_mul_f32_e32 v21, v21, v21
	v_cvt_pk_bf16_f32 v204, v22, v23
	v_cvt_pk_bf16_f32 v205, v24, v25
	v_cvt_pk_bf16_f32 v206, v18, v19
	v_cvt_pk_bf16_f32 v207, v20, v21
	v_permlane16_swap_b32_e32 v200, v202
	v_permlane16_swap_b32_e32 v201, v203
	global_store_dwordx4 v191, v[200:203], s[64:65]
	v_max_f32_e32 v0, v14, v14
	v_max_f32_e32 v14, 0, v0
	v_mul_f32_e32 v14, v14, v14
	v_max_f32_e32 v0, v15, v15
	v_max_f32_e32 v15, 0, v0
	v_mul_f32_e32 v15, v15, v15
	v_max_f32_e32 v0, v16, v16
	v_max_f32_e32 v16, 0, v0
	v_mul_f32_e32 v16, v16, v16
	v_max_f32_e32 v0, v17, v17
	v_max_f32_e32 v17, 0, v0
	v_mul_f32_e32 v17, v17, v17
	v_max_f32_e32 v0, v10, v10
	v_max_f32_e32 v10, 0, v0
	v_mul_f32_e32 v10, v10, v10
	v_max_f32_e32 v0, v11, v11
	v_max_f32_e32 v11, 0, v0
	v_mul_f32_e32 v11, v11, v11
	v_max_f32_e32 v0, v12, v12
	v_max_f32_e32 v12, 0, v0
	v_mul_f32_e32 v12, v12, v12
	v_max_f32_e32 v0, v13, v13
	v_max_f32_e32 v13, 0, v0
	v_mul_f32_e32 v13, v13, v13
	v_cvt_pk_bf16_f32 v208, v14, v15
	v_cvt_pk_bf16_f32 v209, v16, v17
	v_cvt_pk_bf16_f32 v210, v10, v11
	v_cvt_pk_bf16_f32 v211, v12, v13
	v_permlane16_swap_b32_e32 v204, v206
	v_permlane16_swap_b32_e32 v205, v207
	global_store_dwordx4 v191, v[204:207], s[64:65] offset:64
	s_add_u32 s64, s64, s60
	s_addc_u32 s65, s65, 0
	v_max_f32_e32 v0, v2, v2
	v_max_f32_e32 v2, 0, v0
	v_mul_f32_e32 v2, v2, v2
	v_max_f32_e32 v0, v3, v3
	v_max_f32_e32 v3, 0, v0
	v_mul_f32_e32 v3, v3, v3
	v_max_f32_e32 v0, v4, v4
	v_max_f32_e32 v4, 0, v0
	v_mul_f32_e32 v4, v4, v4
	v_max_f32_e32 v0, v5, v5
	v_max_f32_e32 v5, 0, v0
	v_mul_f32_e32 v5, v5, v5
	v_max_f32_e32 v0, v6, v6
	v_max_f32_e32 v6, 0, v0
	v_mul_f32_e32 v6, v6, v6
	v_max_f32_e32 v0, v7, v7
	v_max_f32_e32 v7, 0, v0
	v_mul_f32_e32 v7, v7, v7
	v_max_f32_e32 v0, v8, v8
	v_max_f32_e32 v8, 0, v0
	v_mul_f32_e32 v8, v8, v8
	v_max_f32_e32 v0, v9, v9
	v_max_f32_e32 v9, 0, v0
	v_mul_f32_e32 v9, v9, v9
	v_cvt_pk_bf16_f32 v228, v2, v3
	v_cvt_pk_bf16_f32 v229, v4, v5
	v_cvt_pk_bf16_f32 v230, v6, v7
	v_cvt_pk_bf16_f32 v231, v8, v9
	v_permlane16_swap_b32_e32 v208, v210
	v_permlane16_swap_b32_e32 v209, v211
	global_store_dwordx4 v191, v[208:211], s[64:65]
	s_nop 1
	v_permlane16_swap_b32_e32 v228, v230
	v_permlane16_swap_b32_e32 v229, v231
	global_store_dwordx4 v191, v[228:231], s[64:65] offset:64
	s_branch .LBB0_888
.Lmy_stage:
	s_cbranch_vccz .LBB0_900
	s_nop 0
	v_cvt_pk_bf16_f32 v130, v126, v127
	v_cvt_pk_bf16_f32 v131, v128, v129
	s_mov_b64 s[28:29], 0
